# row-statistics exchanges (P7 x2, P9): drop the cache invalidate after the counter wait; the slot loads that follow are agent-scope sc1 loads and nothing else read afterwards is produced by peers in th
# speedup vs baseline: 1.0024x; 1.0024x over previous
;     __device__ __forceinline__ bool run(const f32x4 (&v)[2][2][4][2], const Unit& u, int wr, int wc, int fr, int fq, PG8_LAS unsigned char* lds, int wid, int lane) const {
;     ...
;         if (wid == 0) {
;             bool dead = false; const unsigned long long t0 = __builtin_amdgcn_s_memrealtime(); const unsigned want = 8u * (unsigned)ntn;
;             for (;;) {
;     ...
;                 break;
;     ...
;                 if ((unsigned)__builtin_amdgcn_readfirstlane(__hip_atomic_load(cnt + 64 * u.pm, __ATOMIC_RELAXED, __HIP_MEMORY_SCOPE_AGENT)) >= want) break;
;                 if (__builtin_amdgcn_s_memrealtime() - t0 > 2000000ull) {
;                     if (lane == 0) { unsigned expect = 0u; __hip_atomic_compare_exchange_strong(tmo + 1, &expect, code | (unsigned)(u.pm & 0xff), __ATOMIC_RELAXED, __ATOMIC_RELAXED, __HIP_MEMORY_SCOPE_AGENT);
;                                      __hip_atomic_store(tmo, 1u, __ATOMIC_RELAXED, __HIP_MEMORY_SCOPE_AGENT); }
;                     dead = true; break; }
;                 __builtin_amdgcn_s_sleep(2);
;             }
;             __builtin_amdgcn_fence(__ATOMIC_ACQUIRE, "agent");
;             if (lane == 0) flag[0] = dead ? 1u : 0u;
.LBB0_1068:
	s_waitcnt vmcnt(0)
	s_and_b64 exec, exec, s[8:9]
	v_cndmask_b32_e64 v148, 0, 1, s[12:13]
	v_mov_b32_e32 v149, 0
	ds_write_b32 v149, v148 offset:10240

;     __device__ __forceinline__ bool run(const f32x4 (&v)[2][2][4][2], const Unit& u, int wr, int wc, int fr, int fq, PG8_LAS unsigned char* lds, int wid, int lane) const {
;     ...
;         if (wid == 0) {
;             bool dead = false; const unsigned long long t0 = __builtin_amdgcn_s_memrealtime(); const unsigned want = 8u * (unsigned)ntn;
;             for (;;) {
;     ...
;                 break;
;     ...
;                 if ((unsigned)__builtin_amdgcn_readfirstlane(__hip_atomic_load(cnt + 64 * u.pm, __ATOMIC_RELAXED, __HIP_MEMORY_SCOPE_AGENT)) >= want) break;
;                 if (__builtin_amdgcn_s_memrealtime() - t0 > 2000000ull) {
;                     if (lane == 0) { unsigned expect = 0u; __hip_atomic_compare_exchange_strong(tmo + 1, &expect, code | (unsigned)(u.pm & 0xff), __ATOMIC_RELAXED, __ATOMIC_RELAXED, __HIP_MEMORY_SCOPE_AGENT);
;                                      __hip_atomic_store(tmo, 1u, __ATOMIC_RELAXED, __HIP_MEMORY_SCOPE_AGENT); }
;                     dead = true; break; }
;                 __builtin_amdgcn_s_sleep(2);
;             }
;             __builtin_amdgcn_fence(__ATOMIC_ACQUIRE, "agent");
;             if (lane == 0) flag[0] = dead ? 1u : 0u;
.LBB0_1108:
	s_waitcnt vmcnt(0)
	s_and_b64 exec, exec, s[8:9]
	v_cndmask_b32_e64 v130, 0, 1, s[10:11]
	v_mov_b32_e32 v131, 0
	ds_write_b32 v131, v130 offset:10240

;     __device__ __forceinline__ bool run(const f32x4 (&v)[2][2][4][2], const Unit& u, int wr, int wc, int fr, int fq, PG8_LAS unsigned char* lds, int wid, int lane) const {
;     ...
;         if (wid == 0) {
;             bool dead = false; const unsigned long long t0 = __builtin_amdgcn_s_memrealtime(); const unsigned want = 8u * (unsigned)ntn;
;             for (;;) {
;     ...
;                 break;
;     ...
;                 if ((unsigned)__builtin_amdgcn_readfirstlane(__hip_atomic_load(cnt + 64 * u.pm, __ATOMIC_RELAXED, __HIP_MEMORY_SCOPE_AGENT)) >= want) break;
;                 if (__builtin_amdgcn_s_memrealtime() - t0 > 2000000ull) {
;                     if (lane == 0) { unsigned expect = 0u; __hip_atomic_compare_exchange_strong(tmo + 1, &expect, code | (unsigned)(u.pm & 0xff), __ATOMIC_RELAXED, __ATOMIC_RELAXED, __HIP_MEMORY_SCOPE_AGENT);
;                                      __hip_atomic_store(tmo, 1u, __ATOMIC_RELAXED, __HIP_MEMORY_SCOPE_AGENT); }
;                     dead = true; break; }
;                 __builtin_amdgcn_s_sleep(2);
;             }
;             __builtin_amdgcn_fence(__ATOMIC_ACQUIRE, "agent");
;             if (lane == 0) flag[0] = dead ? 1u : 0u;
.LBB0_1299:
	s_waitcnt vmcnt(0)
	s_and_b64 exec, exec, s[2:3]
	v_cndmask_b32_e64 v216, 0, 1, s[8:9]
	v_mov_b32_e32 v217, 0
	ds_write_b32 v217, v216 offset:10240
